# peeled first K-iteration per GEMM unit: first-touch MFMAs take srcC=0, the 128-v_mov accumulator zeroing block per unit removed (on top of v46)
# speedup vs baseline: 1.0004x; 1.0004x over previous
.LBB0_208:
	s_ashr_i32 s11, s10, 31
	s_lshl_b64 s[12:13], s[10:11], 20
	s_add_u32 s12, s24, s12
	s_addc_u32 s13, s25, s13
	s_and_b64 s[14:15], s[0:1], exec
	s_cselect_b32 s11, s13, s17
	s_cselect_b32 s40, s12, s16
	s_ashr_i32 s9, s8, 31
	s_lshl_b64 s[14:15], s[8:9], 20
	s_add_u32 s14, s26, s14
	s_addc_u32 s15, s27, s15
	s_and_b64 s[20:21], s[0:1], exec
	s_cselect_b32 s9, s15, s19
	s_cselect_b32 s41, s14, s18
	s_add_u32 s16, s16, 0x80080
	s_addc_u32 s17, s17, 0
	s_add_u32 s42, s18, 0x100
	s_addc_u32 s43, s19, 0
	s_mov_b32 s44, -2
	s_add_u32 s18, s16, 0xfff80080
	s_addc_u32 s19, s17, -1
	s_add_i32 s45, s93, 0x100
	s_cmp_eq_u32 s44, 28
	s_cselect_b32 s21, s11, s19
	s_cselect_b32 s20, s40, s18
	s_cselect_b32 s19, s9, s43
	s_cselect_b32 s18, s41, s42
	s_add_i32 s49, s62, 0x100
	v_add_u32_e32 v156, s45, v131
	v_add_u32_e32 v172, s49, v131
	ds_read_b128 v[142:145], v156
	ds_read_b128 v[148:151], v156 offset:1024
	ds_read_b128 v[152:155], v156 offset:2048
	ds_read_b128 v[156:159], v156 offset:3072
	ds_read_b128 v[160:163], v172
	ds_read_b128 v[164:167], v172 offset:1024
	ds_read_b128 v[168:171], v172 offset:2048
	ds_read_b128 v[172:175], v172 offset:3072
	v_lshl_add_u64 v[180:181], s[16:17], 0, v[138:139]
	s_add_i32 m0, s29, 0xc000
	ds_read_b128 v[184:187], v147
	ds_read_b128 v[188:191], v147 offset:1024
	ds_read_b128 v[192:195], v147 offset:2048
	ds_read_b128 v[196:199], v147 offset:3072
	ds_read_b128 v[200:203], v147 offset:4096
	ds_read_b128 v[204:207], v147 offset:5120
	ds_read_b128 v[226:229], v147 offset:6144
	ds_read_b128 v[230:233], v147 offset:7168
	global_load_lds_dwordx4 v[180:181], off
	v_lshl_add_u64 v[180:181], s[16:17], 0, v[140:141]
	s_add_i32 m0, s29, 0xe000
	s_nop 0
	global_load_lds_dwordx4 v[180:181], off
	s_waitcnt vmcnt(8)
	s_waitcnt lgkmcnt(0)
	s_barrier
	s_setprio 1
	s_waitcnt lgkmcnt(0)
	v_mfma_f32_16x16x32_bf16 v[124:127], v[142:145], v[184:187], 0
	v_mfma_f32_16x16x32_bf16 v[120:123], v[152:155], v[184:187], 0
	v_mfma_f32_16x16x32_bf16 v[116:119], v[142:145], v[192:195], 0
	v_mfma_f32_16x16x32_bf16 v[108:111], v[152:155], v[192:195], 0
	v_mfma_f32_16x16x32_bf16 v[100:103], v[142:145], v[200:203], 0
	v_mfma_f32_16x16x32_bf16 v[92:95], v[152:155], v[200:203], 0
	v_mfma_f32_16x16x32_bf16 v[84:87], v[142:145], v[226:229], 0
	v_mfma_f32_16x16x32_bf16 v[76:79], v[152:155], v[226:229], 0
	v_mfma_f32_16x16x32_bf16 v[124:127], v[148:151], v[188:191], v[124:127]
	v_mfma_f32_16x16x32_bf16 v[120:123], v[156:159], v[188:191], v[120:123]
	v_mfma_f32_16x16x32_bf16 v[116:119], v[148:151], v[196:199], v[116:119]
	v_mfma_f32_16x16x32_bf16 v[108:111], v[156:159], v[196:199], v[108:111]
	v_mfma_f32_16x16x32_bf16 v[100:103], v[148:151], v[204:207], v[100:103]
	v_mfma_f32_16x16x32_bf16 v[92:95], v[156:159], v[204:207], v[92:95]
	v_mfma_f32_16x16x32_bf16 v[84:87], v[148:151], v[230:233], v[84:87]
	v_mfma_f32_16x16x32_bf16 v[76:79], v[156:159], v[230:233], v[76:79]
	s_setprio 0
	s_setprio 1
	v_mfma_f32_16x16x32_bf16 v[112:115], v[160:163], v[184:187], 0
	v_mfma_f32_16x16x32_bf16 v[104:107], v[168:171], v[184:187], 0
	v_mfma_f32_16x16x32_bf16 v[96:99], v[160:163], v[192:195], 0
	v_mfma_f32_16x16x32_bf16 v[88:91], v[168:171], v[192:195], 0
	v_mfma_f32_16x16x32_bf16 v[80:83], v[160:163], v[200:203], 0
	v_mfma_f32_16x16x32_bf16 v[72:75], v[168:171], v[200:203], 0
	v_mfma_f32_16x16x32_bf16 v[68:71], v[160:163], v[226:229], 0
	v_mfma_f32_16x16x32_bf16 v[64:67], v[168:171], v[226:229], 0
	v_mfma_f32_16x16x32_bf16 v[112:115], v[164:167], v[188:191], v[112:115]
	v_mfma_f32_16x16x32_bf16 v[104:107], v[172:175], v[188:191], v[104:107]
	v_mfma_f32_16x16x32_bf16 v[96:99], v[164:167], v[196:199], v[96:99]
	v_mfma_f32_16x16x32_bf16 v[88:91], v[172:175], v[196:199], v[88:91]
	v_mfma_f32_16x16x32_bf16 v[80:83], v[164:167], v[204:207], v[80:83]
	v_mfma_f32_16x16x32_bf16 v[72:75], v[172:175], v[204:207], v[72:75]
	v_mfma_f32_16x16x32_bf16 v[68:71], v[164:167], v[230:233], v[68:71]
	v_mfma_f32_16x16x32_bf16 v[64:67], v[172:175], v[230:233], v[64:67]
	s_setprio 0
	s_barrier
	s_add_i32 s45, s45, s28
	v_lshl_add_u64 v[180:181], s[18:19], 0, v[178:179]
	s_mov_b32 m0, s45
	ds_read_b128 v[184:187], v147 offset:16384
	ds_read_b128 v[188:191], v147 offset:17408
	ds_read_b128 v[192:195], v147 offset:18432
	ds_read_b128 v[196:199], v147 offset:19456
	ds_read_b128 v[200:203], v147 offset:20480
	ds_read_b128 v[204:207], v147 offset:21504
	ds_read_b128 v[226:229], v147 offset:22528
	ds_read_b128 v[230:233], v147 offset:23552
	global_load_lds_dwordx4 v[180:181], off
	s_add_i32 m0, s45, 0x2000
	s_add_u32 s46, s18, 0x80000
	v_lshl_add_u64 v[182:183], s[18:19], 0, v[132:133]
	s_addc_u32 s47, s19, 0
	s_add_i32 s45, s49, s28
	global_load_lds_dwordx4 v[182:183], off
	v_lshl_add_u64 v[208:209], s[46:47], 0, v[178:179]
	s_mov_b32 m0, s45
	v_lshl_add_u64 v[210:211], s[20:21], 0, v[134:135]
	global_load_lds_dwordx4 v[208:209], off
	v_lshl_add_u64 v[208:209], s[46:47], 0, v[132:133]
	s_add_i32 m0, s45, 0x2000
	s_nop 0
	global_load_lds_dwordx4 v[208:209], off
	v_lshl_add_u64 v[208:209], s[20:21], 0, v[136:137]
	s_mov_b32 m0, s29
	s_nop 0
	global_load_lds_dwordx4 v[208:209], off
	s_mov_b32 m0, s30
	s_nop 0
	global_load_lds_dwordx4 v[210:211], off
	s_waitcnt vmcnt(8)
	s_waitcnt lgkmcnt(0)
	s_barrier
	s_setprio 1
	s_waitcnt lgkmcnt(0)
	v_mfma_f32_16x16x32_bf16 v[60:63], v[142:145], v[184:187], 0
	v_mfma_f32_16x16x32_bf16 v[56:59], v[152:155], v[184:187], 0
	v_mfma_f32_16x16x32_bf16 v[52:55], v[142:145], v[192:195], 0
	v_mfma_f32_16x16x32_bf16 v[44:47], v[152:155], v[192:195], 0
	v_mfma_f32_16x16x32_bf16 v[36:39], v[142:145], v[200:203], 0
	v_mfma_f32_16x16x32_bf16 v[28:31], v[152:155], v[200:203], 0
	v_mfma_f32_16x16x32_bf16 v[20:23], v[142:145], v[226:229], 0
	v_mfma_f32_16x16x32_bf16 v[12:15], v[152:155], v[226:229], 0
	v_mfma_f32_16x16x32_bf16 v[60:63], v[148:151], v[188:191], v[60:63]
	v_mfma_f32_16x16x32_bf16 v[56:59], v[156:159], v[188:191], v[56:59]
	v_mfma_f32_16x16x32_bf16 v[52:55], v[148:151], v[196:199], v[52:55]
	v_mfma_f32_16x16x32_bf16 v[44:47], v[156:159], v[196:199], v[44:47]
	v_mfma_f32_16x16x32_bf16 v[36:39], v[148:151], v[204:207], v[36:39]
	v_mfma_f32_16x16x32_bf16 v[28:31], v[156:159], v[204:207], v[28:31]
	v_mfma_f32_16x16x32_bf16 v[20:23], v[148:151], v[230:233], v[20:23]
	v_mfma_f32_16x16x32_bf16 v[12:15], v[156:159], v[230:233], v[12:15]
	s_setprio 0
	s_setprio 1
	v_mfma_f32_16x16x32_bf16 v[48:51], v[160:163], v[184:187], 0
	v_mfma_f32_16x16x32_bf16 v[40:43], v[168:171], v[184:187], 0
	v_mfma_f32_16x16x32_bf16 v[32:35], v[160:163], v[192:195], 0
	v_mfma_f32_16x16x32_bf16 v[24:27], v[168:171], v[192:195], 0
	v_mfma_f32_16x16x32_bf16 v[16:19], v[160:163], v[200:203], 0
	v_mfma_f32_16x16x32_bf16 v[8:11], v[168:171], v[200:203], 0
	v_mfma_f32_16x16x32_bf16 v[4:7], v[160:163], v[226:229], 0
	v_mfma_f32_16x16x32_bf16 v[0:3], v[168:171], v[226:229], 0
	v_mfma_f32_16x16x32_bf16 v[48:51], v[164:167], v[188:191], v[48:51]
	v_mfma_f32_16x16x32_bf16 v[40:43], v[172:175], v[188:191], v[40:43]
	v_mfma_f32_16x16x32_bf16 v[32:35], v[164:167], v[196:199], v[32:35]
	v_mfma_f32_16x16x32_bf16 v[24:27], v[172:175], v[196:199], v[24:27]
	v_mfma_f32_16x16x32_bf16 v[16:19], v[164:167], v[204:207], v[16:19]
	v_mfma_f32_16x16x32_bf16 v[8:11], v[172:175], v[204:207], v[8:11]
	v_mfma_f32_16x16x32_bf16 v[4:7], v[164:167], v[230:233], v[4:7]
	v_mfma_f32_16x16x32_bf16 v[0:3], v[172:175], v[230:233], v[0:3]
	s_setprio 0
	s_barrier
	s_add_i32 s45, s63, 0x100
	s_add_i32 s46, s75, 0x100
	v_add_u32_e32 v156, s45, v131
	v_add_u32_e32 v172, s46, v131
	ds_read_b128 v[142:145], v156
	ds_read_b128 v[148:151], v156 offset:1024
	ds_read_b128 v[152:155], v156 offset:2048
	ds_read_b128 v[156:159], v156 offset:3072
	ds_read_b128 v[160:163], v172
	ds_read_b128 v[164:167], v172 offset:1024
	ds_read_b128 v[168:171], v172 offset:2048
	ds_read_b128 v[172:175], v172 offset:3072
	s_add_u32 s20, s20, 0x80000
	s_addc_u32 s21, s21, 0
	s_mov_b32 m0, s31
	v_lshl_add_u64 v[212:213], s[20:21], 0, v[136:137]
	ds_read_b128 v[184:187], v147 offset:32768
	ds_read_b128 v[188:191], v147 offset:33792
	ds_read_b128 v[192:195], v147 offset:34816
	ds_read_b128 v[196:199], v147 offset:35840
	ds_read_b128 v[200:203], v147 offset:36864
	ds_read_b128 v[204:207], v147 offset:37888
	ds_read_b128 v[226:229], v147 offset:38912
	ds_read_b128 v[230:233], v147 offset:39936
	global_load_lds_dwordx4 v[212:213], off
	v_lshl_add_u64 v[212:213], s[20:21], 0, v[134:135]
	s_mov_b32 m0, s34
	s_nop 0
	global_load_lds_dwordx4 v[212:213], off
	s_waitcnt vmcnt(8)
	s_waitcnt lgkmcnt(0)
	s_barrier
	s_setprio 1
	s_waitcnt lgkmcnt(0)
	v_mfma_f32_16x16x32_bf16 v[124:127], v[142:145], v[184:187], v[124:127]
	v_mfma_f32_16x16x32_bf16 v[120:123], v[152:155], v[184:187], v[120:123]
	v_mfma_f32_16x16x32_bf16 v[116:119], v[142:145], v[192:195], v[116:119]
	v_mfma_f32_16x16x32_bf16 v[108:111], v[152:155], v[192:195], v[108:111]
	v_mfma_f32_16x16x32_bf16 v[100:103], v[142:145], v[200:203], v[100:103]
	v_mfma_f32_16x16x32_bf16 v[92:95], v[152:155], v[200:203], v[92:95]
	v_mfma_f32_16x16x32_bf16 v[84:87], v[142:145], v[226:229], v[84:87]
	v_mfma_f32_16x16x32_bf16 v[76:79], v[152:155], v[226:229], v[76:79]
	v_mfma_f32_16x16x32_bf16 v[124:127], v[148:151], v[188:191], v[124:127]
	v_mfma_f32_16x16x32_bf16 v[120:123], v[156:159], v[188:191], v[120:123]
	v_mfma_f32_16x16x32_bf16 v[116:119], v[148:151], v[196:199], v[116:119]
	v_mfma_f32_16x16x32_bf16 v[108:111], v[156:159], v[196:199], v[108:111]
	v_mfma_f32_16x16x32_bf16 v[100:103], v[148:151], v[204:207], v[100:103]
	v_mfma_f32_16x16x32_bf16 v[92:95], v[156:159], v[204:207], v[92:95]
	v_mfma_f32_16x16x32_bf16 v[84:87], v[148:151], v[230:233], v[84:87]
	v_mfma_f32_16x16x32_bf16 v[76:79], v[156:159], v[230:233], v[76:79]
	s_setprio 0
	s_setprio 1
	v_mfma_f32_16x16x32_bf16 v[112:115], v[160:163], v[184:187], v[112:115]
	v_mfma_f32_16x16x32_bf16 v[104:107], v[168:171], v[184:187], v[104:107]
	v_mfma_f32_16x16x32_bf16 v[96:99], v[160:163], v[192:195], v[96:99]
	v_mfma_f32_16x16x32_bf16 v[88:91], v[168:171], v[192:195], v[88:91]
	v_mfma_f32_16x16x32_bf16 v[80:83], v[160:163], v[200:203], v[80:83]
	v_mfma_f32_16x16x32_bf16 v[72:75], v[168:171], v[200:203], v[72:75]
	v_mfma_f32_16x16x32_bf16 v[68:71], v[160:163], v[226:229], v[68:71]
	v_mfma_f32_16x16x32_bf16 v[64:67], v[168:171], v[226:229], v[64:67]
	v_mfma_f32_16x16x32_bf16 v[112:115], v[164:167], v[188:191], v[112:115]
	v_mfma_f32_16x16x32_bf16 v[104:107], v[172:175], v[188:191], v[104:107]
	v_mfma_f32_16x16x32_bf16 v[96:99], v[164:167], v[196:199], v[96:99]
	v_mfma_f32_16x16x32_bf16 v[88:91], v[172:175], v[196:199], v[88:91]
	v_mfma_f32_16x16x32_bf16 v[80:83], v[164:167], v[204:207], v[80:83]
	v_mfma_f32_16x16x32_bf16 v[72:75], v[172:175], v[204:207], v[72:75]
	v_mfma_f32_16x16x32_bf16 v[68:71], v[164:167], v[230:233], v[68:71]
	v_mfma_f32_16x16x32_bf16 v[64:67], v[172:175], v[230:233], v[64:67]
	s_setprio 0
	s_barrier
	s_add_i32 s20, s45, s28
	v_lshl_add_u64 v[180:181], v[180:181], 0, s[78:79]
	s_mov_b32 m0, s20
	ds_read_b128 v[184:187], v147 offset:49152
	ds_read_b128 v[188:191], v147 offset:50176
	ds_read_b128 v[192:195], v147 offset:51200
	ds_read_b128 v[196:199], v147 offset:52224
	ds_read_b128 v[200:203], v147 offset:53248
	ds_read_b128 v[204:207], v147 offset:54272
	ds_read_b128 v[226:229], v147 offset:55296
	ds_read_b128 v[230:233], v147 offset:56320
	global_load_lds_dwordx4 v[180:181], off
	s_add_i32 m0, s20, 0x2000
	s_add_u32 s18, s18, 0x80080
	v_lshl_add_u64 v[180:181], v[182:183], 0, s[78:79]
	s_addc_u32 s19, s19, 0
	s_add_i32 s20, s46, s28
	global_load_lds_dwordx4 v[180:181], off
	v_lshl_add_u64 v[180:181], s[18:19], 0, v[178:179]
	s_mov_b32 m0, s20
	s_nop 0
	global_load_lds_dwordx4 v[180:181], off
	v_lshl_add_u64 v[180:181], s[18:19], 0, v[132:133]
	s_add_i32 m0, s20, 0x2000
	s_nop 0
	global_load_lds_dwordx4 v[180:181], off
	v_lshl_add_u64 v[180:181], v[208:209], 0, s[78:79]
	s_mov_b32 m0, s35
	s_nop 0
	global_load_lds_dwordx4 v[180:181], off
	v_lshl_add_u64 v[180:181], v[210:211], 0, s[78:79]
	s_mov_b32 m0, s36
	s_nop 0
	global_load_lds_dwordx4 v[180:181], off
	s_waitcnt vmcnt(8)
	s_waitcnt lgkmcnt(0)
	s_barrier
	s_setprio 1
	s_waitcnt lgkmcnt(0)
	v_mfma_f32_16x16x32_bf16 v[60:63], v[142:145], v[184:187], v[60:63]
	v_mfma_f32_16x16x32_bf16 v[56:59], v[152:155], v[184:187], v[56:59]
	v_mfma_f32_16x16x32_bf16 v[52:55], v[142:145], v[192:195], v[52:55]
	v_mfma_f32_16x16x32_bf16 v[44:47], v[152:155], v[192:195], v[44:47]
	v_mfma_f32_16x16x32_bf16 v[36:39], v[142:145], v[200:203], v[36:39]
	v_mfma_f32_16x16x32_bf16 v[28:31], v[152:155], v[200:203], v[28:31]
	v_mfma_f32_16x16x32_bf16 v[20:23], v[142:145], v[226:229], v[20:23]
	v_mfma_f32_16x16x32_bf16 v[12:15], v[152:155], v[226:229], v[12:15]
	v_mfma_f32_16x16x32_bf16 v[60:63], v[148:151], v[188:191], v[60:63]
	v_mfma_f32_16x16x32_bf16 v[56:59], v[156:159], v[188:191], v[56:59]
	v_mfma_f32_16x16x32_bf16 v[52:55], v[148:151], v[196:199], v[52:55]
	v_mfma_f32_16x16x32_bf16 v[44:47], v[156:159], v[196:199], v[44:47]
	v_mfma_f32_16x16x32_bf16 v[36:39], v[148:151], v[204:207], v[36:39]
	v_mfma_f32_16x16x32_bf16 v[28:31], v[156:159], v[204:207], v[28:31]
	v_mfma_f32_16x16x32_bf16 v[20:23], v[148:151], v[230:233], v[20:23]
	v_mfma_f32_16x16x32_bf16 v[12:15], v[156:159], v[230:233], v[12:15]
	s_setprio 0
	s_setprio 1
	v_mfma_f32_16x16x32_bf16 v[48:51], v[160:163], v[184:187], v[48:51]
	v_mfma_f32_16x16x32_bf16 v[40:43], v[168:171], v[184:187], v[40:43]
	v_mfma_f32_16x16x32_bf16 v[32:35], v[160:163], v[192:195], v[32:35]
	v_mfma_f32_16x16x32_bf16 v[24:27], v[168:171], v[192:195], v[24:27]
	v_mfma_f32_16x16x32_bf16 v[16:19], v[160:163], v[200:203], v[16:19]
	v_mfma_f32_16x16x32_bf16 v[8:11], v[168:171], v[200:203], v[8:11]
	v_mfma_f32_16x16x32_bf16 v[4:7], v[160:163], v[226:229], v[4:7]
	v_mfma_f32_16x16x32_bf16 v[0:3], v[168:171], v[226:229], v[0:3]
	v_mfma_f32_16x16x32_bf16 v[48:51], v[164:167], v[188:191], v[48:51]
	v_mfma_f32_16x16x32_bf16 v[40:43], v[172:175], v[188:191], v[40:43]
	v_mfma_f32_16x16x32_bf16 v[32:35], v[164:167], v[196:199], v[32:35]
	v_mfma_f32_16x16x32_bf16 v[24:27], v[172:175], v[196:199], v[24:27]
	v_mfma_f32_16x16x32_bf16 v[16:19], v[164:167], v[204:207], v[16:19]
	v_mfma_f32_16x16x32_bf16 v[8:11], v[172:175], v[204:207], v[8:11]
	v_mfma_f32_16x16x32_bf16 v[4:7], v[164:167], v[230:233], v[4:7]
	v_mfma_f32_16x16x32_bf16 v[0:3], v[172:175], v[230:233], v[0:3]
	s_setprio 0
	s_barrier
	s_add_i32 s44, s44, 2
	s_add_u32 s16, s16, 0x100
	s_addc_u32 s17, s17, 0
	s_add_u32 s42, s42, 0x100
	s_addc_u32 s43, s43, 0
	s_cmp_gt_u32 s44, 29

.LBB0_833:
	s_ashr_i32 s13, s12, 31
	s_lshl_b64 s[14:15], s[12:13], 20
	s_add_u32 s14, s24, s14
	s_addc_u32 s15, s25, s15
	s_and_b64 s[16:17], s[0:1], exec
	s_cselect_b32 s13, s15, s19
	s_cselect_b32 s40, s14, s18
	s_ashr_i32 s11, s10, 31
	s_lshl_b64 s[16:17], s[10:11], 20
	s_add_u32 s16, s26, s16
	s_addc_u32 s17, s27, s17
	s_and_b64 s[22:23], s[0:1], exec
	s_cselect_b32 s11, s17, s21
	s_cselect_b32 s41, s16, s20
	s_add_u32 s18, s18, 0x80080
	s_addc_u32 s19, s19, 0
	s_add_u32 s42, s20, 0x100
	s_addc_u32 s43, s21, 0
	s_mov_b32 s44, -2
	s_add_u32 s20, s18, 0xfff80080
	s_addc_u32 s21, s19, -1
	s_add_i32 s45, s93, 0x100
	s_cmp_eq_u32 s44, 28
	s_cselect_b32 s23, s13, s21
	s_cselect_b32 s22, s40, s20
	v_add_u32_e32 v140, s45, v142
	s_cselect_b32 s21, s11, s43
	s_cselect_b32 s20, s41, s42
	s_add_i32 s49, s62, 0x100
	ds_read_b128 v[146:149], v140
	ds_read_b128 v[150:153], v140 offset:1024
	ds_read_b128 v[154:157], v140 offset:2048
	ds_read_b128 v[158:161], v140 offset:3072
	v_add_u32_e32 v140, s49, v142
	ds_read_b128 v[162:165], v140
	ds_read_b128 v[166:169], v140 offset:1024
	ds_read_b128 v[170:173], v140 offset:2048
	ds_read_b128 v[180:183], v140 offset:3072
	v_lshl_add_u64 v[140:141], s[18:19], 0, v[136:137]
	s_add_i32 m0, s29, 0xc000
	ds_read_b128 v[184:187], v144
	ds_read_b128 v[188:191], v144 offset:1024
	ds_read_b128 v[192:195], v144 offset:2048
	ds_read_b128 v[196:199], v144 offset:3072
	ds_read_b128 v[200:203], v144 offset:4096
	ds_read_b128 v[204:207], v144 offset:5120
	ds_read_b128 v[208:211], v144 offset:6144
	ds_read_b128 v[226:229], v144 offset:7168
	global_load_lds_dwordx4 v[140:141], off
	v_lshl_add_u64 v[140:141], s[18:19], 0, v[138:139]
	s_add_i32 m0, s29, 0xe000
	s_nop 0
	global_load_lds_dwordx4 v[140:141], off
	s_waitcnt vmcnt(8)
	s_waitcnt lgkmcnt(0)
	s_barrier
	s_setprio 1
	s_waitcnt lgkmcnt(0)
	v_mfma_f32_16x16x32_bf16 v[124:127], v[146:149], v[184:187], 0
	v_mfma_f32_16x16x32_bf16 v[120:123], v[154:157], v[184:187], 0
	v_mfma_f32_16x16x32_bf16 v[116:119], v[146:149], v[192:195], 0
	v_mfma_f32_16x16x32_bf16 v[108:111], v[154:157], v[192:195], 0
	v_mfma_f32_16x16x32_bf16 v[100:103], v[146:149], v[200:203], 0
	v_mfma_f32_16x16x32_bf16 v[92:95], v[154:157], v[200:203], 0
	v_mfma_f32_16x16x32_bf16 v[84:87], v[146:149], v[208:211], 0
	v_mfma_f32_16x16x32_bf16 v[76:79], v[154:157], v[208:211], 0
	v_mfma_f32_16x16x32_bf16 v[124:127], v[150:153], v[188:191], v[124:127]
	v_mfma_f32_16x16x32_bf16 v[120:123], v[158:161], v[188:191], v[120:123]
	v_mfma_f32_16x16x32_bf16 v[116:119], v[150:153], v[196:199], v[116:119]
	v_mfma_f32_16x16x32_bf16 v[108:111], v[158:161], v[196:199], v[108:111]
	v_mfma_f32_16x16x32_bf16 v[100:103], v[150:153], v[204:207], v[100:103]
	v_mfma_f32_16x16x32_bf16 v[92:95], v[158:161], v[204:207], v[92:95]
	v_mfma_f32_16x16x32_bf16 v[84:87], v[150:153], v[226:229], v[84:87]
	v_mfma_f32_16x16x32_bf16 v[76:79], v[158:161], v[226:229], v[76:79]
	s_setprio 0
	s_setprio 1
	v_mfma_f32_16x16x32_bf16 v[112:115], v[162:165], v[184:187], 0
	v_mfma_f32_16x16x32_bf16 v[104:107], v[170:173], v[184:187], 0
	v_mfma_f32_16x16x32_bf16 v[96:99], v[162:165], v[192:195], 0
	v_mfma_f32_16x16x32_bf16 v[88:91], v[170:173], v[192:195], 0
	v_mfma_f32_16x16x32_bf16 v[80:83], v[162:165], v[200:203], 0
	v_mfma_f32_16x16x32_bf16 v[72:75], v[170:173], v[200:203], 0
	v_mfma_f32_16x16x32_bf16 v[68:71], v[162:165], v[208:211], 0
	v_mfma_f32_16x16x32_bf16 v[64:67], v[170:173], v[208:211], 0
	v_mfma_f32_16x16x32_bf16 v[112:115], v[166:169], v[188:191], v[112:115]
	v_mfma_f32_16x16x32_bf16 v[104:107], v[180:183], v[188:191], v[104:107]
	v_mfma_f32_16x16x32_bf16 v[96:99], v[166:169], v[196:199], v[96:99]
	v_mfma_f32_16x16x32_bf16 v[88:91], v[180:183], v[196:199], v[88:91]
	v_mfma_f32_16x16x32_bf16 v[80:83], v[166:169], v[204:207], v[80:83]
	v_mfma_f32_16x16x32_bf16 v[72:75], v[180:183], v[204:207], v[72:75]
	v_mfma_f32_16x16x32_bf16 v[68:71], v[166:169], v[226:229], v[68:71]
	v_mfma_f32_16x16x32_bf16 v[64:67], v[180:183], v[226:229], v[64:67]
	s_setprio 0
	s_barrier
	s_add_i32 s45, s45, s28
	v_lshl_add_u64 v[140:141], s[20:21], 0, v[178:179]
	s_mov_b32 m0, s45
	ds_read_b128 v[184:187], v144 offset:16384
	ds_read_b128 v[188:191], v144 offset:17408
	ds_read_b128 v[192:195], v144 offset:18432
	ds_read_b128 v[196:199], v144 offset:19456
	ds_read_b128 v[200:203], v144 offset:20480
	ds_read_b128 v[204:207], v144 offset:21504
	ds_read_b128 v[208:211], v144 offset:22528
	ds_read_b128 v[226:229], v144 offset:23552
	global_load_lds_dwordx4 v[140:141], off
	s_add_i32 m0, s45, 0x2000
	s_add_u32 s46, s20, 0x80000
	v_lshl_add_u64 v[174:175], s[20:21], 0, v[130:131]
	s_addc_u32 s47, s21, 0
	s_add_i32 s45, s49, s28
	global_load_lds_dwordx4 v[174:175], off
	v_lshl_add_u64 v[212:213], s[46:47], 0, v[178:179]
	s_mov_b32 m0, s45
	v_lshl_add_u64 v[230:231], s[22:23], 0, v[132:133]
	global_load_lds_dwordx4 v[212:213], off
	v_lshl_add_u64 v[212:213], s[46:47], 0, v[130:131]
	s_add_i32 m0, s45, 0x2000
	s_nop 0
	global_load_lds_dwordx4 v[212:213], off
	v_lshl_add_u64 v[212:213], s[22:23], 0, v[134:135]
	s_mov_b32 m0, s29
	s_nop 0
	global_load_lds_dwordx4 v[212:213], off
	s_mov_b32 m0, s30
	s_nop 0
	global_load_lds_dwordx4 v[230:231], off
	s_waitcnt vmcnt(8)
	s_waitcnt lgkmcnt(0)
	s_barrier
	s_setprio 1
	s_waitcnt lgkmcnt(0)
	v_mfma_f32_16x16x32_bf16 v[60:63], v[146:149], v[184:187], 0
	v_mfma_f32_16x16x32_bf16 v[56:59], v[154:157], v[184:187], 0
	v_mfma_f32_16x16x32_bf16 v[52:55], v[146:149], v[192:195], 0
	v_mfma_f32_16x16x32_bf16 v[44:47], v[154:157], v[192:195], 0
	v_mfma_f32_16x16x32_bf16 v[36:39], v[146:149], v[200:203], 0
	v_mfma_f32_16x16x32_bf16 v[28:31], v[154:157], v[200:203], 0
	v_mfma_f32_16x16x32_bf16 v[20:23], v[146:149], v[208:211], 0
	v_mfma_f32_16x16x32_bf16 v[12:15], v[154:157], v[208:211], 0
	v_mfma_f32_16x16x32_bf16 v[60:63], v[150:153], v[188:191], v[60:63]
	v_mfma_f32_16x16x32_bf16 v[56:59], v[158:161], v[188:191], v[56:59]
	v_mfma_f32_16x16x32_bf16 v[52:55], v[150:153], v[196:199], v[52:55]
	v_mfma_f32_16x16x32_bf16 v[44:47], v[158:161], v[196:199], v[44:47]
	v_mfma_f32_16x16x32_bf16 v[36:39], v[150:153], v[204:207], v[36:39]
	v_mfma_f32_16x16x32_bf16 v[28:31], v[158:161], v[204:207], v[28:31]
	v_mfma_f32_16x16x32_bf16 v[20:23], v[150:153], v[226:229], v[20:23]
	v_mfma_f32_16x16x32_bf16 v[12:15], v[158:161], v[226:229], v[12:15]
	s_setprio 0
	s_setprio 1
	v_mfma_f32_16x16x32_bf16 v[48:51], v[162:165], v[184:187], 0
	v_mfma_f32_16x16x32_bf16 v[40:43], v[170:173], v[184:187], 0
	v_mfma_f32_16x16x32_bf16 v[32:35], v[162:165], v[192:195], 0
	v_mfma_f32_16x16x32_bf16 v[24:27], v[170:173], v[192:195], 0
	v_mfma_f32_16x16x32_bf16 v[16:19], v[162:165], v[200:203], 0
	v_mfma_f32_16x16x32_bf16 v[8:11], v[170:173], v[200:203], 0
	v_mfma_f32_16x16x32_bf16 v[4:7], v[162:165], v[208:211], 0
	v_mfma_f32_16x16x32_bf16 v[0:3], v[170:173], v[208:211], 0
	v_mfma_f32_16x16x32_bf16 v[48:51], v[166:169], v[188:191], v[48:51]
	v_mfma_f32_16x16x32_bf16 v[40:43], v[180:183], v[188:191], v[40:43]
	v_mfma_f32_16x16x32_bf16 v[32:35], v[166:169], v[196:199], v[32:35]
	v_mfma_f32_16x16x32_bf16 v[24:27], v[180:183], v[196:199], v[24:27]
	v_mfma_f32_16x16x32_bf16 v[16:19], v[166:169], v[204:207], v[16:19]
	v_mfma_f32_16x16x32_bf16 v[8:11], v[180:183], v[204:207], v[8:11]
	v_mfma_f32_16x16x32_bf16 v[4:7], v[166:169], v[226:229], v[4:7]
	v_mfma_f32_16x16x32_bf16 v[0:3], v[180:183], v[226:229], v[0:3]
	s_setprio 0
	s_barrier
	s_add_i32 s45, s63, 0x100
	v_add_u32_e32 v145, s45, v142
	s_add_i32 s46, s75, 0x100
	ds_read_b128 v[146:149], v145
	ds_read_b128 v[150:153], v145 offset:1024
	ds_read_b128 v[154:157], v145 offset:2048
	ds_read_b128 v[158:161], v145 offset:3072
	v_add_u32_e32 v145, s46, v142
	ds_read_b128 v[162:165], v145
	ds_read_b128 v[166:169], v145 offset:1024
	ds_read_b128 v[170:173], v145 offset:2048
	ds_read_b128 v[180:183], v145 offset:3072
	s_add_u32 s22, s22, 0x80000
	s_addc_u32 s23, s23, 0
	s_mov_b32 m0, s31
	v_lshl_add_u64 v[232:233], s[22:23], 0, v[134:135]
	ds_read_b128 v[184:187], v144 offset:32768
	ds_read_b128 v[188:191], v144 offset:33792
	ds_read_b128 v[192:195], v144 offset:34816
	ds_read_b128 v[196:199], v144 offset:35840
	ds_read_b128 v[200:203], v144 offset:36864
	ds_read_b128 v[204:207], v144 offset:37888
	ds_read_b128 v[208:211], v144 offset:38912
	ds_read_b128 v[226:229], v144 offset:39936
	global_load_lds_dwordx4 v[232:233], off
	v_lshl_add_u64 v[232:233], s[22:23], 0, v[132:133]
	s_mov_b32 m0, s34
	s_nop 0
	global_load_lds_dwordx4 v[232:233], off
	s_waitcnt vmcnt(8)
	s_waitcnt lgkmcnt(0)
	s_barrier
	s_setprio 1
	s_waitcnt lgkmcnt(0)
	v_mfma_f32_16x16x32_bf16 v[124:127], v[146:149], v[184:187], v[124:127]
	v_mfma_f32_16x16x32_bf16 v[120:123], v[154:157], v[184:187], v[120:123]
	v_mfma_f32_16x16x32_bf16 v[116:119], v[146:149], v[192:195], v[116:119]
	v_mfma_f32_16x16x32_bf16 v[108:111], v[154:157], v[192:195], v[108:111]
	v_mfma_f32_16x16x32_bf16 v[100:103], v[146:149], v[200:203], v[100:103]
	v_mfma_f32_16x16x32_bf16 v[92:95], v[154:157], v[200:203], v[92:95]
	v_mfma_f32_16x16x32_bf16 v[84:87], v[146:149], v[208:211], v[84:87]
	v_mfma_f32_16x16x32_bf16 v[76:79], v[154:157], v[208:211], v[76:79]
	v_mfma_f32_16x16x32_bf16 v[124:127], v[150:153], v[188:191], v[124:127]
	v_mfma_f32_16x16x32_bf16 v[120:123], v[158:161], v[188:191], v[120:123]
	v_mfma_f32_16x16x32_bf16 v[116:119], v[150:153], v[196:199], v[116:119]
	v_mfma_f32_16x16x32_bf16 v[108:111], v[158:161], v[196:199], v[108:111]
	v_mfma_f32_16x16x32_bf16 v[100:103], v[150:153], v[204:207], v[100:103]
	v_mfma_f32_16x16x32_bf16 v[92:95], v[158:161], v[204:207], v[92:95]
	v_mfma_f32_16x16x32_bf16 v[84:87], v[150:153], v[226:229], v[84:87]
	v_mfma_f32_16x16x32_bf16 v[76:79], v[158:161], v[226:229], v[76:79]
	s_setprio 0
	s_setprio 1
	v_mfma_f32_16x16x32_bf16 v[112:115], v[162:165], v[184:187], v[112:115]
	v_mfma_f32_16x16x32_bf16 v[104:107], v[170:173], v[184:187], v[104:107]
	v_mfma_f32_16x16x32_bf16 v[96:99], v[162:165], v[192:195], v[96:99]
	v_mfma_f32_16x16x32_bf16 v[88:91], v[170:173], v[192:195], v[88:91]
	v_mfma_f32_16x16x32_bf16 v[80:83], v[162:165], v[200:203], v[80:83]
	v_mfma_f32_16x16x32_bf16 v[72:75], v[170:173], v[200:203], v[72:75]
	v_mfma_f32_16x16x32_bf16 v[68:71], v[162:165], v[208:211], v[68:71]
	v_mfma_f32_16x16x32_bf16 v[64:67], v[170:173], v[208:211], v[64:67]
	v_mfma_f32_16x16x32_bf16 v[112:115], v[166:169], v[188:191], v[112:115]
	v_mfma_f32_16x16x32_bf16 v[104:107], v[180:183], v[188:191], v[104:107]
	v_mfma_f32_16x16x32_bf16 v[96:99], v[166:169], v[196:199], v[96:99]
	v_mfma_f32_16x16x32_bf16 v[88:91], v[180:183], v[196:199], v[88:91]
	v_mfma_f32_16x16x32_bf16 v[80:83], v[166:169], v[204:207], v[80:83]
	v_mfma_f32_16x16x32_bf16 v[72:75], v[180:183], v[204:207], v[72:75]
	v_mfma_f32_16x16x32_bf16 v[68:71], v[166:169], v[226:229], v[68:71]
	v_mfma_f32_16x16x32_bf16 v[64:67], v[180:183], v[226:229], v[64:67]
	s_setprio 0
	s_barrier
	s_add_i32 s22, s45, s28
	v_lshl_add_u64 v[140:141], v[140:141], 0, s[78:79]
	s_mov_b32 m0, s22
	ds_read_b128 v[184:187], v144 offset:49152
	ds_read_b128 v[188:191], v144 offset:50176
	ds_read_b128 v[192:195], v144 offset:51200
	ds_read_b128 v[196:199], v144 offset:52224
	ds_read_b128 v[200:203], v144 offset:53248
	ds_read_b128 v[204:207], v144 offset:54272
	ds_read_b128 v[208:211], v144 offset:55296
	ds_read_b128 v[226:229], v144 offset:56320
	global_load_lds_dwordx4 v[140:141], off
	s_add_i32 m0, s22, 0x2000
	s_add_u32 s20, s20, 0x80080
	v_lshl_add_u64 v[140:141], v[174:175], 0, s[78:79]
	s_addc_u32 s21, s21, 0
	s_add_i32 s22, s46, s28
	global_load_lds_dwordx4 v[140:141], off
	v_lshl_add_u64 v[140:141], s[20:21], 0, v[178:179]
	s_mov_b32 m0, s22
	s_nop 0
	global_load_lds_dwordx4 v[140:141], off
	v_lshl_add_u64 v[140:141], s[20:21], 0, v[130:131]
	s_add_i32 m0, s22, 0x2000
	s_nop 0
	global_load_lds_dwordx4 v[140:141], off
	v_lshl_add_u64 v[140:141], v[212:213], 0, s[78:79]
	s_mov_b32 m0, s35
	s_nop 0
	global_load_lds_dwordx4 v[140:141], off
	v_lshl_add_u64 v[140:141], v[230:231], 0, s[78:79]
	s_mov_b32 m0, s36
	s_nop 0
	global_load_lds_dwordx4 v[140:141], off
	s_waitcnt vmcnt(8)
	s_waitcnt lgkmcnt(0)
	s_barrier
	s_setprio 1
	s_waitcnt lgkmcnt(0)
	v_mfma_f32_16x16x32_bf16 v[60:63], v[146:149], v[184:187], v[60:63]
	v_mfma_f32_16x16x32_bf16 v[56:59], v[154:157], v[184:187], v[56:59]
	v_mfma_f32_16x16x32_bf16 v[52:55], v[146:149], v[192:195], v[52:55]
	v_mfma_f32_16x16x32_bf16 v[44:47], v[154:157], v[192:195], v[44:47]
	v_mfma_f32_16x16x32_bf16 v[36:39], v[146:149], v[200:203], v[36:39]
	v_mfma_f32_16x16x32_bf16 v[28:31], v[154:157], v[200:203], v[28:31]
	v_mfma_f32_16x16x32_bf16 v[20:23], v[146:149], v[208:211], v[20:23]
	v_mfma_f32_16x16x32_bf16 v[12:15], v[154:157], v[208:211], v[12:15]
	v_mfma_f32_16x16x32_bf16 v[60:63], v[150:153], v[188:191], v[60:63]
	v_mfma_f32_16x16x32_bf16 v[56:59], v[158:161], v[188:191], v[56:59]
	v_mfma_f32_16x16x32_bf16 v[52:55], v[150:153], v[196:199], v[52:55]
	v_mfma_f32_16x16x32_bf16 v[44:47], v[158:161], v[196:199], v[44:47]
	v_mfma_f32_16x16x32_bf16 v[36:39], v[150:153], v[204:207], v[36:39]
	v_mfma_f32_16x16x32_bf16 v[28:31], v[158:161], v[204:207], v[28:31]
	v_mfma_f32_16x16x32_bf16 v[20:23], v[150:153], v[226:229], v[20:23]
	v_mfma_f32_16x16x32_bf16 v[12:15], v[158:161], v[226:229], v[12:15]
	s_setprio 0
	s_setprio 1
	v_mfma_f32_16x16x32_bf16 v[48:51], v[162:165], v[184:187], v[48:51]
	v_mfma_f32_16x16x32_bf16 v[40:43], v[170:173], v[184:187], v[40:43]
	v_mfma_f32_16x16x32_bf16 v[32:35], v[162:165], v[192:195], v[32:35]
	v_mfma_f32_16x16x32_bf16 v[24:27], v[170:173], v[192:195], v[24:27]
	v_mfma_f32_16x16x32_bf16 v[16:19], v[162:165], v[200:203], v[16:19]
	v_mfma_f32_16x16x32_bf16 v[8:11], v[170:173], v[200:203], v[8:11]
	v_mfma_f32_16x16x32_bf16 v[4:7], v[162:165], v[208:211], v[4:7]
	v_mfma_f32_16x16x32_bf16 v[0:3], v[170:173], v[208:211], v[0:3]
	v_mfma_f32_16x16x32_bf16 v[48:51], v[166:169], v[188:191], v[48:51]
	v_mfma_f32_16x16x32_bf16 v[40:43], v[180:183], v[188:191], v[40:43]
	v_mfma_f32_16x16x32_bf16 v[32:35], v[166:169], v[196:199], v[32:35]
	v_mfma_f32_16x16x32_bf16 v[24:27], v[180:183], v[196:199], v[24:27]
	v_mfma_f32_16x16x32_bf16 v[16:19], v[166:169], v[204:207], v[16:19]
	v_mfma_f32_16x16x32_bf16 v[8:11], v[180:183], v[204:207], v[8:11]
	v_mfma_f32_16x16x32_bf16 v[4:7], v[166:169], v[226:229], v[4:7]
	v_mfma_f32_16x16x32_bf16 v[0:3], v[180:183], v[226:229], v[0:3]
	s_setprio 0
	s_barrier
	s_add_i32 s44, s44, 2
	s_add_u32 s18, s18, 0x100
	s_addc_u32 s19, s19, 0
	s_add_u32 s42, s42, 0x100
	s_addc_u32 s43, s43, 0
	s_cmp_gt_u32 s44, 29

.LBB0_1025:
	s_ashr_i32 s15, s14, 31
	s_lshl_b64 s[16:17], s[14:15], 20
	s_add_u32 s16, s26, s16
	s_addc_u32 s17, s27, s17
	s_and_b64 s[18:19], s[0:1], exec
	s_cselect_b32 s15, s17, s21
	s_cselect_b32 s42, s16, s20
	s_ashr_i32 s13, s12, 31
	s_lshl_b64 s[18:19], s[12:13], 20
	s_add_u32 s18, s28, s18
	s_addc_u32 s19, s29, s19
	s_and_b64 s[24:25], s[0:1], exec
	s_cselect_b32 s13, s19, s23
	s_cselect_b32 s43, s18, s22
	s_add_u32 s20, s20, 0x80080
	s_addc_u32 s21, s21, 0
	s_add_u32 s44, s22, 0x100
	s_addc_u32 s45, s23, 0
	s_mov_b32 s46, -2
	s_add_u32 s22, s20, 0xfff80080
	s_addc_u32 s23, s21, -1
	s_add_i32 s47, s93, 0x100
	s_cmp_eq_u32 s46, 28
	s_cselect_b32 s25, s15, s23
	s_cselect_b32 s24, s42, s22
	v_add_u32_e32 v140, s47, v142
	s_cselect_b32 s23, s13, s45
	s_cselect_b32 s22, s43, s44
	s_add_i32 s49, s62, 0x100
	ds_read_b128 v[146:149], v140
	ds_read_b128 v[150:153], v140 offset:1024
	ds_read_b128 v[154:157], v140 offset:2048
	ds_read_b128 v[158:161], v140 offset:3072
	v_add_u32_e32 v140, s49, v142
	ds_read_b128 v[162:165], v140
	ds_read_b128 v[166:169], v140 offset:1024
	ds_read_b128 v[170:173], v140 offset:2048
	ds_read_b128 v[180:183], v140 offset:3072
	v_lshl_add_u64 v[140:141], s[20:21], 0, v[136:137]
	s_add_i32 m0, s31, 0xc000
	ds_read_b128 v[184:187], v144
	ds_read_b128 v[188:191], v144 offset:1024
	ds_read_b128 v[192:195], v144 offset:2048
	ds_read_b128 v[196:199], v144 offset:3072
	ds_read_b128 v[200:203], v144 offset:4096
	ds_read_b128 v[204:207], v144 offset:5120
	ds_read_b128 v[208:211], v144 offset:6144
	ds_read_b128 v[226:229], v144 offset:7168
	global_load_lds_dwordx4 v[140:141], off
	v_lshl_add_u64 v[140:141], s[20:21], 0, v[138:139]
	s_add_i32 m0, s31, 0xe000
	s_nop 0
	global_load_lds_dwordx4 v[140:141], off
	s_waitcnt vmcnt(8)
	s_waitcnt lgkmcnt(0)
	s_barrier
	s_setprio 1
	s_waitcnt lgkmcnt(0)
	v_mfma_f32_16x16x32_bf16 v[124:127], v[146:149], v[184:187], 0
	v_mfma_f32_16x16x32_bf16 v[120:123], v[154:157], v[184:187], 0
	v_mfma_f32_16x16x32_bf16 v[108:111], v[146:149], v[192:195], 0
	v_mfma_f32_16x16x32_bf16 v[104:107], v[154:157], v[192:195], 0
	v_mfma_f32_16x16x32_bf16 v[92:95], v[146:149], v[200:203], 0
	v_mfma_f32_16x16x32_bf16 v[88:91], v[154:157], v[200:203], 0
	v_mfma_f32_16x16x32_bf16 v[76:79], v[146:149], v[208:211], 0
	v_mfma_f32_16x16x32_bf16 v[72:75], v[154:157], v[208:211], 0
	v_mfma_f32_16x16x32_bf16 v[124:127], v[150:153], v[188:191], v[124:127]
	v_mfma_f32_16x16x32_bf16 v[120:123], v[158:161], v[188:191], v[120:123]
	v_mfma_f32_16x16x32_bf16 v[108:111], v[150:153], v[196:199], v[108:111]
	v_mfma_f32_16x16x32_bf16 v[104:107], v[158:161], v[196:199], v[104:107]
	v_mfma_f32_16x16x32_bf16 v[92:95], v[150:153], v[204:207], v[92:95]
	v_mfma_f32_16x16x32_bf16 v[88:91], v[158:161], v[204:207], v[88:91]
	v_mfma_f32_16x16x32_bf16 v[76:79], v[150:153], v[226:229], v[76:79]
	v_mfma_f32_16x16x32_bf16 v[72:75], v[158:161], v[226:229], v[72:75]
	s_setprio 0
	s_setprio 1
	v_mfma_f32_16x16x32_bf16 v[116:119], v[162:165], v[184:187], 0
	v_mfma_f32_16x16x32_bf16 v[112:115], v[170:173], v[184:187], 0
	v_mfma_f32_16x16x32_bf16 v[100:103], v[162:165], v[192:195], 0
	v_mfma_f32_16x16x32_bf16 v[96:99], v[170:173], v[192:195], 0
	v_mfma_f32_16x16x32_bf16 v[84:87], v[162:165], v[200:203], 0
	v_mfma_f32_16x16x32_bf16 v[80:83], v[170:173], v[200:203], 0
	v_mfma_f32_16x16x32_bf16 v[68:71], v[162:165], v[208:211], 0
	v_mfma_f32_16x16x32_bf16 v[64:67], v[170:173], v[208:211], 0
	v_mfma_f32_16x16x32_bf16 v[116:119], v[166:169], v[188:191], v[116:119]
	v_mfma_f32_16x16x32_bf16 v[112:115], v[180:183], v[188:191], v[112:115]
	v_mfma_f32_16x16x32_bf16 v[100:103], v[166:169], v[196:199], v[100:103]
	v_mfma_f32_16x16x32_bf16 v[96:99], v[180:183], v[196:199], v[96:99]
	v_mfma_f32_16x16x32_bf16 v[84:87], v[166:169], v[204:207], v[84:87]
	v_mfma_f32_16x16x32_bf16 v[80:83], v[180:183], v[204:207], v[80:83]
	v_mfma_f32_16x16x32_bf16 v[68:71], v[166:169], v[226:229], v[68:71]
	v_mfma_f32_16x16x32_bf16 v[64:67], v[180:183], v[226:229], v[64:67]
	s_setprio 0
	s_barrier
	s_add_i32 s47, s47, s30
	v_lshl_add_u64 v[140:141], s[22:23], 0, v[178:179]
	s_mov_b32 m0, s47
	ds_read_b128 v[184:187], v144 offset:16384
	ds_read_b128 v[188:191], v144 offset:17408
	ds_read_b128 v[192:195], v144 offset:18432
	ds_read_b128 v[196:199], v144 offset:19456
	ds_read_b128 v[200:203], v144 offset:20480
	ds_read_b128 v[204:207], v144 offset:21504
	ds_read_b128 v[208:211], v144 offset:22528
	ds_read_b128 v[226:229], v144 offset:23552
	global_load_lds_dwordx4 v[140:141], off
	s_add_i32 m0, s47, 0x2000
	s_add_u32 s50, s22, 0x80000
	v_lshl_add_u64 v[174:175], s[22:23], 0, v[130:131]
	s_addc_u32 s51, s23, 0
	s_add_i32 s47, s49, s30
	global_load_lds_dwordx4 v[174:175], off
	v_lshl_add_u64 v[212:213], s[50:51], 0, v[178:179]
	s_mov_b32 m0, s47
	v_lshl_add_u64 v[230:231], s[24:25], 0, v[132:133]
	global_load_lds_dwordx4 v[212:213], off
	v_lshl_add_u64 v[212:213], s[50:51], 0, v[130:131]
	s_add_i32 m0, s47, 0x2000
	s_nop 0
	global_load_lds_dwordx4 v[212:213], off
	v_lshl_add_u64 v[212:213], s[24:25], 0, v[134:135]
	s_mov_b32 m0, s31
	s_nop 0
	global_load_lds_dwordx4 v[212:213], off
	s_mov_b32 m0, s34
	s_nop 0
	global_load_lds_dwordx4 v[230:231], off
	s_waitcnt vmcnt(8)
	s_waitcnt lgkmcnt(0)
	s_barrier
	s_setprio 1
	s_waitcnt lgkmcnt(0)
	v_mfma_f32_16x16x32_bf16 v[60:63], v[146:149], v[184:187], 0
	v_mfma_f32_16x16x32_bf16 v[56:59], v[154:157], v[184:187], 0
	v_mfma_f32_16x16x32_bf16 v[44:47], v[146:149], v[192:195], 0
	v_mfma_f32_16x16x32_bf16 v[40:43], v[154:157], v[192:195], 0
	v_mfma_f32_16x16x32_bf16 v[28:31], v[146:149], v[200:203], 0
	v_mfma_f32_16x16x32_bf16 v[24:27], v[154:157], v[200:203], 0
	v_mfma_f32_16x16x32_bf16 v[12:15], v[146:149], v[208:211], 0
	v_mfma_f32_16x16x32_bf16 v[8:11], v[154:157], v[208:211], 0
	v_mfma_f32_16x16x32_bf16 v[60:63], v[150:153], v[188:191], v[60:63]
	v_mfma_f32_16x16x32_bf16 v[56:59], v[158:161], v[188:191], v[56:59]
	v_mfma_f32_16x16x32_bf16 v[44:47], v[150:153], v[196:199], v[44:47]
	v_mfma_f32_16x16x32_bf16 v[40:43], v[158:161], v[196:199], v[40:43]
	v_mfma_f32_16x16x32_bf16 v[28:31], v[150:153], v[204:207], v[28:31]
	v_mfma_f32_16x16x32_bf16 v[24:27], v[158:161], v[204:207], v[24:27]
	v_mfma_f32_16x16x32_bf16 v[12:15], v[150:153], v[226:229], v[12:15]
	v_mfma_f32_16x16x32_bf16 v[8:11], v[158:161], v[226:229], v[8:11]
	s_setprio 0
	s_setprio 1
	v_mfma_f32_16x16x32_bf16 v[52:55], v[162:165], v[184:187], 0
	v_mfma_f32_16x16x32_bf16 v[48:51], v[170:173], v[184:187], 0
	v_mfma_f32_16x16x32_bf16 v[36:39], v[162:165], v[192:195], 0
	v_mfma_f32_16x16x32_bf16 v[32:35], v[170:173], v[192:195], 0
	v_mfma_f32_16x16x32_bf16 v[20:23], v[162:165], v[200:203], 0
	v_mfma_f32_16x16x32_bf16 v[16:19], v[170:173], v[200:203], 0
	v_mfma_f32_16x16x32_bf16 v[4:7], v[162:165], v[208:211], 0
	v_mfma_f32_16x16x32_bf16 v[0:3], v[170:173], v[208:211], 0
	v_mfma_f32_16x16x32_bf16 v[52:55], v[166:169], v[188:191], v[52:55]
	v_mfma_f32_16x16x32_bf16 v[48:51], v[180:183], v[188:191], v[48:51]
	v_mfma_f32_16x16x32_bf16 v[36:39], v[166:169], v[196:199], v[36:39]
	v_mfma_f32_16x16x32_bf16 v[32:35], v[180:183], v[196:199], v[32:35]
	v_mfma_f32_16x16x32_bf16 v[20:23], v[166:169], v[204:207], v[20:23]
	v_mfma_f32_16x16x32_bf16 v[16:19], v[180:183], v[204:207], v[16:19]
	v_mfma_f32_16x16x32_bf16 v[4:7], v[166:169], v[226:229], v[4:7]
	v_mfma_f32_16x16x32_bf16 v[0:3], v[180:183], v[226:229], v[0:3]
	s_setprio 0
	s_barrier
	s_add_i32 s47, s63, 0x100
	v_add_u32_e32 v145, s47, v142
	s_add_i32 s49, s75, 0x100
	ds_read_b128 v[146:149], v145
	ds_read_b128 v[150:153], v145 offset:1024
	ds_read_b128 v[154:157], v145 offset:2048
	ds_read_b128 v[158:161], v145 offset:3072
	v_add_u32_e32 v145, s49, v142
	ds_read_b128 v[162:165], v145
	ds_read_b128 v[166:169], v145 offset:1024
	ds_read_b128 v[170:173], v145 offset:2048
	ds_read_b128 v[180:183], v145 offset:3072
	s_add_u32 s24, s24, 0x80000
	s_addc_u32 s25, s25, 0
	s_mov_b32 m0, s35
	v_lshl_add_u64 v[232:233], s[24:25], 0, v[134:135]
	ds_read_b128 v[184:187], v144 offset:32768
	ds_read_b128 v[188:191], v144 offset:33792
	ds_read_b128 v[192:195], v144 offset:34816
	ds_read_b128 v[196:199], v144 offset:35840
	ds_read_b128 v[200:203], v144 offset:36864
	ds_read_b128 v[204:207], v144 offset:37888
	ds_read_b128 v[208:211], v144 offset:38912
	ds_read_b128 v[226:229], v144 offset:39936
	global_load_lds_dwordx4 v[232:233], off
	v_lshl_add_u64 v[232:233], s[24:25], 0, v[132:133]
	s_mov_b32 m0, s36
	s_nop 0
	global_load_lds_dwordx4 v[232:233], off
	s_waitcnt vmcnt(8)
	s_waitcnt lgkmcnt(0)
	s_barrier
	s_setprio 1
	s_waitcnt lgkmcnt(0)
	v_mfma_f32_16x16x32_bf16 v[124:127], v[146:149], v[184:187], v[124:127]
	v_mfma_f32_16x16x32_bf16 v[120:123], v[154:157], v[184:187], v[120:123]
	v_mfma_f32_16x16x32_bf16 v[108:111], v[146:149], v[192:195], v[108:111]
	v_mfma_f32_16x16x32_bf16 v[104:107], v[154:157], v[192:195], v[104:107]
	v_mfma_f32_16x16x32_bf16 v[92:95], v[146:149], v[200:203], v[92:95]
	v_mfma_f32_16x16x32_bf16 v[88:91], v[154:157], v[200:203], v[88:91]
	v_mfma_f32_16x16x32_bf16 v[76:79], v[146:149], v[208:211], v[76:79]
	v_mfma_f32_16x16x32_bf16 v[72:75], v[154:157], v[208:211], v[72:75]
	v_mfma_f32_16x16x32_bf16 v[124:127], v[150:153], v[188:191], v[124:127]
	v_mfma_f32_16x16x32_bf16 v[120:123], v[158:161], v[188:191], v[120:123]
	v_mfma_f32_16x16x32_bf16 v[108:111], v[150:153], v[196:199], v[108:111]
	v_mfma_f32_16x16x32_bf16 v[104:107], v[158:161], v[196:199], v[104:107]
	v_mfma_f32_16x16x32_bf16 v[92:95], v[150:153], v[204:207], v[92:95]
	v_mfma_f32_16x16x32_bf16 v[88:91], v[158:161], v[204:207], v[88:91]
	v_mfma_f32_16x16x32_bf16 v[76:79], v[150:153], v[226:229], v[76:79]
	v_mfma_f32_16x16x32_bf16 v[72:75], v[158:161], v[226:229], v[72:75]
	s_setprio 0
	s_setprio 1
	v_mfma_f32_16x16x32_bf16 v[116:119], v[162:165], v[184:187], v[116:119]
	v_mfma_f32_16x16x32_bf16 v[112:115], v[170:173], v[184:187], v[112:115]
	v_mfma_f32_16x16x32_bf16 v[100:103], v[162:165], v[192:195], v[100:103]
	v_mfma_f32_16x16x32_bf16 v[96:99], v[170:173], v[192:195], v[96:99]
	v_mfma_f32_16x16x32_bf16 v[84:87], v[162:165], v[200:203], v[84:87]
	v_mfma_f32_16x16x32_bf16 v[80:83], v[170:173], v[200:203], v[80:83]
	v_mfma_f32_16x16x32_bf16 v[68:71], v[162:165], v[208:211], v[68:71]
	v_mfma_f32_16x16x32_bf16 v[64:67], v[170:173], v[208:211], v[64:67]
	v_mfma_f32_16x16x32_bf16 v[116:119], v[166:169], v[188:191], v[116:119]
	v_mfma_f32_16x16x32_bf16 v[112:115], v[180:183], v[188:191], v[112:115]
	v_mfma_f32_16x16x32_bf16 v[100:103], v[166:169], v[196:199], v[100:103]
	v_mfma_f32_16x16x32_bf16 v[96:99], v[180:183], v[196:199], v[96:99]
	v_mfma_f32_16x16x32_bf16 v[84:87], v[166:169], v[204:207], v[84:87]
	v_mfma_f32_16x16x32_bf16 v[80:83], v[180:183], v[204:207], v[80:83]
	v_mfma_f32_16x16x32_bf16 v[68:71], v[166:169], v[226:229], v[68:71]
	v_mfma_f32_16x16x32_bf16 v[64:67], v[180:183], v[226:229], v[64:67]
	s_setprio 0
	s_barrier
	s_add_i32 s24, s47, s30
	v_lshl_add_u64 v[140:141], v[140:141], 0, s[78:79]
	s_mov_b32 m0, s24
	ds_read_b128 v[184:187], v144 offset:49152
	ds_read_b128 v[188:191], v144 offset:50176
	ds_read_b128 v[192:195], v144 offset:51200
	ds_read_b128 v[196:199], v144 offset:52224
	ds_read_b128 v[200:203], v144 offset:53248
	ds_read_b128 v[204:207], v144 offset:54272
	ds_read_b128 v[208:211], v144 offset:55296
	ds_read_b128 v[226:229], v144 offset:56320
	global_load_lds_dwordx4 v[140:141], off
	s_add_i32 m0, s24, 0x2000
	s_add_u32 s22, s22, 0x80080
	v_lshl_add_u64 v[140:141], v[174:175], 0, s[78:79]
	s_addc_u32 s23, s23, 0
	s_add_i32 s24, s49, s30
	global_load_lds_dwordx4 v[140:141], off
	v_lshl_add_u64 v[140:141], s[22:23], 0, v[178:179]
	s_mov_b32 m0, s24
	s_nop 0
	global_load_lds_dwordx4 v[140:141], off
	v_lshl_add_u64 v[140:141], s[22:23], 0, v[130:131]
	s_add_i32 m0, s24, 0x2000
	s_nop 0
	global_load_lds_dwordx4 v[140:141], off
	v_lshl_add_u64 v[140:141], v[212:213], 0, s[78:79]
	s_mov_b32 m0, s37
	s_nop 0
	global_load_lds_dwordx4 v[140:141], off
	v_lshl_add_u64 v[140:141], v[230:231], 0, s[78:79]
	s_mov_b32 m0, s38
	s_nop 0
	global_load_lds_dwordx4 v[140:141], off
	s_waitcnt vmcnt(8)
	s_waitcnt lgkmcnt(0)
	s_barrier
	s_setprio 1
	s_waitcnt lgkmcnt(0)
	v_mfma_f32_16x16x32_bf16 v[60:63], v[146:149], v[184:187], v[60:63]
	v_mfma_f32_16x16x32_bf16 v[56:59], v[154:157], v[184:187], v[56:59]
	v_mfma_f32_16x16x32_bf16 v[44:47], v[146:149], v[192:195], v[44:47]
	v_mfma_f32_16x16x32_bf16 v[40:43], v[154:157], v[192:195], v[40:43]
	v_mfma_f32_16x16x32_bf16 v[28:31], v[146:149], v[200:203], v[28:31]
	v_mfma_f32_16x16x32_bf16 v[24:27], v[154:157], v[200:203], v[24:27]
	v_mfma_f32_16x16x32_bf16 v[12:15], v[146:149], v[208:211], v[12:15]
	v_mfma_f32_16x16x32_bf16 v[8:11], v[154:157], v[208:211], v[8:11]
	v_mfma_f32_16x16x32_bf16 v[60:63], v[150:153], v[188:191], v[60:63]
	v_mfma_f32_16x16x32_bf16 v[56:59], v[158:161], v[188:191], v[56:59]
	v_mfma_f32_16x16x32_bf16 v[44:47], v[150:153], v[196:199], v[44:47]
	v_mfma_f32_16x16x32_bf16 v[40:43], v[158:161], v[196:199], v[40:43]
	v_mfma_f32_16x16x32_bf16 v[28:31], v[150:153], v[204:207], v[28:31]
	v_mfma_f32_16x16x32_bf16 v[24:27], v[158:161], v[204:207], v[24:27]
	v_mfma_f32_16x16x32_bf16 v[12:15], v[150:153], v[226:229], v[12:15]
	v_mfma_f32_16x16x32_bf16 v[8:11], v[158:161], v[226:229], v[8:11]
	s_setprio 0
	s_setprio 1
	v_mfma_f32_16x16x32_bf16 v[52:55], v[162:165], v[184:187], v[52:55]
	v_mfma_f32_16x16x32_bf16 v[48:51], v[170:173], v[184:187], v[48:51]
	v_mfma_f32_16x16x32_bf16 v[36:39], v[162:165], v[192:195], v[36:39]
	v_mfma_f32_16x16x32_bf16 v[32:35], v[170:173], v[192:195], v[32:35]
	v_mfma_f32_16x16x32_bf16 v[20:23], v[162:165], v[200:203], v[20:23]
	v_mfma_f32_16x16x32_bf16 v[16:19], v[170:173], v[200:203], v[16:19]
	v_mfma_f32_16x16x32_bf16 v[4:7], v[162:165], v[208:211], v[4:7]
	v_mfma_f32_16x16x32_bf16 v[0:3], v[170:173], v[208:211], v[0:3]
	v_mfma_f32_16x16x32_bf16 v[52:55], v[166:169], v[188:191], v[52:55]
	v_mfma_f32_16x16x32_bf16 v[48:51], v[180:183], v[188:191], v[48:51]
	v_mfma_f32_16x16x32_bf16 v[36:39], v[166:169], v[196:199], v[36:39]
	v_mfma_f32_16x16x32_bf16 v[32:35], v[180:183], v[196:199], v[32:35]
	v_mfma_f32_16x16x32_bf16 v[20:23], v[166:169], v[204:207], v[20:23]
	v_mfma_f32_16x16x32_bf16 v[16:19], v[180:183], v[204:207], v[16:19]
	v_mfma_f32_16x16x32_bf16 v[4:7], v[166:169], v[226:229], v[4:7]
	v_mfma_f32_16x16x32_bf16 v[0:3], v[180:183], v[226:229], v[0:3]
	s_setprio 0
	s_barrier
	s_add_i32 s46, s46, 2
	s_add_u32 s20, s20, 0x100
	s_addc_u32 s21, s21, 0
	s_add_u32 s44, s44, 0x100
	s_addc_u32 s45, s45, 0
	s_cmp_gt_u32 s46, 29

.LBB0_1119:
	s_ashr_i32 s13, s12, 31
	s_lshl_b64 s[14:15], s[12:13], 22
	s_add_u32 s14, s24, s14
	s_addc_u32 s15, s25, s15
	s_and_b64 s[16:17], s[0:1], exec
	s_cselect_b32 s13, s15, s19
	s_cselect_b32 s40, s14, s18
	s_ashr_i32 s11, s10, 31
	s_lshl_b64 s[16:17], s[10:11], 22
	s_add_u32 s16, s26, s16
	s_addc_u32 s17, s27, s17
	s_and_b64 s[22:23], s[0:1], exec
	s_cselect_b32 s11, s17, s21
	s_cselect_b32 s41, s16, s20
	s_add_u32 s18, s18, 0x200080
	s_addc_u32 s19, s19, 0
	s_add_u32 s42, s20, 0x100
	s_addc_u32 s43, s21, 0
	s_mov_b32 s44, -2
	s_add_u32 s20, s18, 0xffe00080
	s_addc_u32 s21, s19, -1
	s_add_i32 s45, s93, 0x100
	s_cmpk_eq_i32 s44, 0x7c
	s_cselect_b32 s23, s13, s21
	s_cselect_b32 s22, s40, s20
	v_add_u32_e32 v140, s45, v142
	s_cselect_b32 s21, s11, s43
	s_cselect_b32 s20, s41, s42
	s_add_i32 s49, s62, 0x100
	ds_read_b128 v[146:149], v140
	ds_read_b128 v[150:153], v140 offset:1024
	ds_read_b128 v[154:157], v140 offset:2048
	ds_read_b128 v[158:161], v140 offset:3072
	v_add_u32_e32 v140, s49, v142
	ds_read_b128 v[162:165], v140
	ds_read_b128 v[166:169], v140 offset:1024
	ds_read_b128 v[170:173], v140 offset:2048
	ds_read_b128 v[180:183], v140 offset:3072
	v_lshl_add_u64 v[140:141], s[18:19], 0, v[136:137]
	s_add_i32 m0, s29, 0xc000
	ds_read_b128 v[184:187], v144
	ds_read_b128 v[188:191], v144 offset:1024
	ds_read_b128 v[192:195], v144 offset:2048
	ds_read_b128 v[196:199], v144 offset:3072
	ds_read_b128 v[200:203], v144 offset:4096
	ds_read_b128 v[204:207], v144 offset:5120
	ds_read_b128 v[208:211], v144 offset:6144
	ds_read_b128 v[226:229], v144 offset:7168
	global_load_lds_dwordx4 v[140:141], off
	v_lshl_add_u64 v[140:141], s[18:19], 0, v[138:139]
	s_add_i32 m0, s29, 0xe000
	s_nop 0
	global_load_lds_dwordx4 v[140:141], off
	s_waitcnt vmcnt(8)
	s_waitcnt lgkmcnt(0)
	s_barrier
	s_setprio 1
	s_waitcnt lgkmcnt(0)
	v_mfma_f32_16x16x32_bf16 v[124:127], v[146:149], v[184:187], 0
	v_mfma_f32_16x16x32_bf16 v[120:123], v[154:157], v[184:187], 0
	v_mfma_f32_16x16x32_bf16 v[116:119], v[146:149], v[192:195], 0
	v_mfma_f32_16x16x32_bf16 v[108:111], v[154:157], v[192:195], 0
	v_mfma_f32_16x16x32_bf16 v[100:103], v[146:149], v[200:203], 0
	v_mfma_f32_16x16x32_bf16 v[92:95], v[154:157], v[200:203], 0
	v_mfma_f32_16x16x32_bf16 v[84:87], v[146:149], v[208:211], 0
	v_mfma_f32_16x16x32_bf16 v[76:79], v[154:157], v[208:211], 0
	v_mfma_f32_16x16x32_bf16 v[124:127], v[150:153], v[188:191], v[124:127]
	v_mfma_f32_16x16x32_bf16 v[120:123], v[158:161], v[188:191], v[120:123]
	v_mfma_f32_16x16x32_bf16 v[116:119], v[150:153], v[196:199], v[116:119]
	v_mfma_f32_16x16x32_bf16 v[108:111], v[158:161], v[196:199], v[108:111]
	v_mfma_f32_16x16x32_bf16 v[100:103], v[150:153], v[204:207], v[100:103]
	v_mfma_f32_16x16x32_bf16 v[92:95], v[158:161], v[204:207], v[92:95]
	v_mfma_f32_16x16x32_bf16 v[84:87], v[150:153], v[226:229], v[84:87]
	v_mfma_f32_16x16x32_bf16 v[76:79], v[158:161], v[226:229], v[76:79]
	s_setprio 0
	s_setprio 1
	v_mfma_f32_16x16x32_bf16 v[112:115], v[162:165], v[184:187], 0
	v_mfma_f32_16x16x32_bf16 v[104:107], v[170:173], v[184:187], 0
	v_mfma_f32_16x16x32_bf16 v[96:99], v[162:165], v[192:195], 0
	v_mfma_f32_16x16x32_bf16 v[88:91], v[170:173], v[192:195], 0
	v_mfma_f32_16x16x32_bf16 v[80:83], v[162:165], v[200:203], 0
	v_mfma_f32_16x16x32_bf16 v[72:75], v[170:173], v[200:203], 0
	v_mfma_f32_16x16x32_bf16 v[68:71], v[162:165], v[208:211], 0
	v_mfma_f32_16x16x32_bf16 v[64:67], v[170:173], v[208:211], 0
	v_mfma_f32_16x16x32_bf16 v[112:115], v[166:169], v[188:191], v[112:115]
	v_mfma_f32_16x16x32_bf16 v[104:107], v[180:183], v[188:191], v[104:107]
	v_mfma_f32_16x16x32_bf16 v[96:99], v[166:169], v[196:199], v[96:99]
	v_mfma_f32_16x16x32_bf16 v[88:91], v[180:183], v[196:199], v[88:91]
	v_mfma_f32_16x16x32_bf16 v[80:83], v[166:169], v[204:207], v[80:83]
	v_mfma_f32_16x16x32_bf16 v[72:75], v[180:183], v[204:207], v[72:75]
	v_mfma_f32_16x16x32_bf16 v[68:71], v[166:169], v[226:229], v[68:71]
	v_mfma_f32_16x16x32_bf16 v[64:67], v[180:183], v[226:229], v[64:67]
	s_setprio 0
	s_barrier
	s_add_i32 s45, s45, s28
	v_lshl_add_u64 v[140:141], s[20:21], 0, v[178:179]
	s_mov_b32 m0, s45
	ds_read_b128 v[184:187], v144 offset:16384
	ds_read_b128 v[188:191], v144 offset:17408
	ds_read_b128 v[192:195], v144 offset:18432
	ds_read_b128 v[196:199], v144 offset:19456
	ds_read_b128 v[200:203], v144 offset:20480
	ds_read_b128 v[204:207], v144 offset:21504
	ds_read_b128 v[208:211], v144 offset:22528
	ds_read_b128 v[226:229], v144 offset:23552
	global_load_lds_dwordx4 v[140:141], off
	s_add_i32 m0, s45, 0x2000
	s_add_u32 s46, s20, 0x200000
	v_lshl_add_u64 v[174:175], s[20:21], 0, v[130:131]
	s_addc_u32 s47, s21, 0
	s_add_i32 s45, s49, s28
	global_load_lds_dwordx4 v[174:175], off
	v_lshl_add_u64 v[212:213], s[46:47], 0, v[178:179]
	s_mov_b32 m0, s45
	v_lshl_add_u64 v[230:231], s[22:23], 0, v[132:133]
	global_load_lds_dwordx4 v[212:213], off
	v_lshl_add_u64 v[212:213], s[46:47], 0, v[130:131]
	s_add_i32 m0, s45, 0x2000
	s_nop 0
	global_load_lds_dwordx4 v[212:213], off
	v_lshl_add_u64 v[212:213], s[22:23], 0, v[134:135]
	s_mov_b32 m0, s29
	s_nop 0
	global_load_lds_dwordx4 v[212:213], off
	s_mov_b32 m0, s30
	s_nop 0
	global_load_lds_dwordx4 v[230:231], off
	s_waitcnt vmcnt(8)
	s_waitcnt lgkmcnt(0)
	s_barrier
	s_setprio 1
	s_waitcnt lgkmcnt(0)
	v_mfma_f32_16x16x32_bf16 v[60:63], v[146:149], v[184:187], 0
	v_mfma_f32_16x16x32_bf16 v[56:59], v[154:157], v[184:187], 0
	v_mfma_f32_16x16x32_bf16 v[52:55], v[146:149], v[192:195], 0
	v_mfma_f32_16x16x32_bf16 v[44:47], v[154:157], v[192:195], 0
	v_mfma_f32_16x16x32_bf16 v[36:39], v[146:149], v[200:203], 0
	v_mfma_f32_16x16x32_bf16 v[28:31], v[154:157], v[200:203], 0
	v_mfma_f32_16x16x32_bf16 v[20:23], v[146:149], v[208:211], 0
	v_mfma_f32_16x16x32_bf16 v[12:15], v[154:157], v[208:211], 0
	v_mfma_f32_16x16x32_bf16 v[60:63], v[150:153], v[188:191], v[60:63]
	v_mfma_f32_16x16x32_bf16 v[56:59], v[158:161], v[188:191], v[56:59]
	v_mfma_f32_16x16x32_bf16 v[52:55], v[150:153], v[196:199], v[52:55]
	v_mfma_f32_16x16x32_bf16 v[44:47], v[158:161], v[196:199], v[44:47]
	v_mfma_f32_16x16x32_bf16 v[36:39], v[150:153], v[204:207], v[36:39]
	v_mfma_f32_16x16x32_bf16 v[28:31], v[158:161], v[204:207], v[28:31]
	v_mfma_f32_16x16x32_bf16 v[20:23], v[150:153], v[226:229], v[20:23]
	v_mfma_f32_16x16x32_bf16 v[12:15], v[158:161], v[226:229], v[12:15]
	s_setprio 0
	s_setprio 1
	v_mfma_f32_16x16x32_bf16 v[48:51], v[162:165], v[184:187], 0
	v_mfma_f32_16x16x32_bf16 v[40:43], v[170:173], v[184:187], 0
	v_mfma_f32_16x16x32_bf16 v[32:35], v[162:165], v[192:195], 0
	v_mfma_f32_16x16x32_bf16 v[24:27], v[170:173], v[192:195], 0
	v_mfma_f32_16x16x32_bf16 v[16:19], v[162:165], v[200:203], 0
	v_mfma_f32_16x16x32_bf16 v[8:11], v[170:173], v[200:203], 0
	v_mfma_f32_16x16x32_bf16 v[4:7], v[162:165], v[208:211], 0
	v_mfma_f32_16x16x32_bf16 v[0:3], v[170:173], v[208:211], 0
	v_mfma_f32_16x16x32_bf16 v[48:51], v[166:169], v[188:191], v[48:51]
	v_mfma_f32_16x16x32_bf16 v[40:43], v[180:183], v[188:191], v[40:43]
	v_mfma_f32_16x16x32_bf16 v[32:35], v[166:169], v[196:199], v[32:35]
	v_mfma_f32_16x16x32_bf16 v[24:27], v[180:183], v[196:199], v[24:27]
	v_mfma_f32_16x16x32_bf16 v[16:19], v[166:169], v[204:207], v[16:19]
	v_mfma_f32_16x16x32_bf16 v[8:11], v[180:183], v[204:207], v[8:11]
	v_mfma_f32_16x16x32_bf16 v[4:7], v[166:169], v[226:229], v[4:7]
	v_mfma_f32_16x16x32_bf16 v[0:3], v[180:183], v[226:229], v[0:3]
	s_setprio 0
	s_barrier
	s_add_i32 s45, s63, 0x100
	v_add_u32_e32 v145, s45, v142
	s_add_i32 s46, s75, 0x100
	ds_read_b128 v[146:149], v145
	ds_read_b128 v[150:153], v145 offset:1024
	ds_read_b128 v[154:157], v145 offset:2048
	ds_read_b128 v[158:161], v145 offset:3072
	v_add_u32_e32 v145, s46, v142
	ds_read_b128 v[162:165], v145
	ds_read_b128 v[166:169], v145 offset:1024
	ds_read_b128 v[170:173], v145 offset:2048
	ds_read_b128 v[180:183], v145 offset:3072
	s_add_u32 s22, s22, 0x200000
	s_addc_u32 s23, s23, 0
	s_mov_b32 m0, s31
	v_lshl_add_u64 v[232:233], s[22:23], 0, v[134:135]
	ds_read_b128 v[184:187], v144 offset:32768
	ds_read_b128 v[188:191], v144 offset:33792
	ds_read_b128 v[192:195], v144 offset:34816
	ds_read_b128 v[196:199], v144 offset:35840
	ds_read_b128 v[200:203], v144 offset:36864
	ds_read_b128 v[204:207], v144 offset:37888
	ds_read_b128 v[208:211], v144 offset:38912
	ds_read_b128 v[226:229], v144 offset:39936
	global_load_lds_dwordx4 v[232:233], off
	v_lshl_add_u64 v[232:233], s[22:23], 0, v[132:133]
	s_mov_b32 m0, s34
	s_nop 0
	global_load_lds_dwordx4 v[232:233], off
	s_waitcnt vmcnt(8)
	s_waitcnt lgkmcnt(0)
	s_barrier
	s_setprio 1
	s_waitcnt lgkmcnt(0)
	v_mfma_f32_16x16x32_bf16 v[124:127], v[146:149], v[184:187], v[124:127]
	v_mfma_f32_16x16x32_bf16 v[120:123], v[154:157], v[184:187], v[120:123]
	v_mfma_f32_16x16x32_bf16 v[116:119], v[146:149], v[192:195], v[116:119]
	v_mfma_f32_16x16x32_bf16 v[108:111], v[154:157], v[192:195], v[108:111]
	v_mfma_f32_16x16x32_bf16 v[100:103], v[146:149], v[200:203], v[100:103]
	v_mfma_f32_16x16x32_bf16 v[92:95], v[154:157], v[200:203], v[92:95]
	v_mfma_f32_16x16x32_bf16 v[84:87], v[146:149], v[208:211], v[84:87]
	v_mfma_f32_16x16x32_bf16 v[76:79], v[154:157], v[208:211], v[76:79]
	v_mfma_f32_16x16x32_bf16 v[124:127], v[150:153], v[188:191], v[124:127]
	v_mfma_f32_16x16x32_bf16 v[120:123], v[158:161], v[188:191], v[120:123]
	v_mfma_f32_16x16x32_bf16 v[116:119], v[150:153], v[196:199], v[116:119]
	v_mfma_f32_16x16x32_bf16 v[108:111], v[158:161], v[196:199], v[108:111]
	v_mfma_f32_16x16x32_bf16 v[100:103], v[150:153], v[204:207], v[100:103]
	v_mfma_f32_16x16x32_bf16 v[92:95], v[158:161], v[204:207], v[92:95]
	v_mfma_f32_16x16x32_bf16 v[84:87], v[150:153], v[226:229], v[84:87]
	v_mfma_f32_16x16x32_bf16 v[76:79], v[158:161], v[226:229], v[76:79]
	s_setprio 0
	s_setprio 1
	v_mfma_f32_16x16x32_bf16 v[112:115], v[162:165], v[184:187], v[112:115]
	v_mfma_f32_16x16x32_bf16 v[104:107], v[170:173], v[184:187], v[104:107]
	v_mfma_f32_16x16x32_bf16 v[96:99], v[162:165], v[192:195], v[96:99]
	v_mfma_f32_16x16x32_bf16 v[88:91], v[170:173], v[192:195], v[88:91]
	v_mfma_f32_16x16x32_bf16 v[80:83], v[162:165], v[200:203], v[80:83]
	v_mfma_f32_16x16x32_bf16 v[72:75], v[170:173], v[200:203], v[72:75]
	v_mfma_f32_16x16x32_bf16 v[68:71], v[162:165], v[208:211], v[68:71]
	v_mfma_f32_16x16x32_bf16 v[64:67], v[170:173], v[208:211], v[64:67]
	v_mfma_f32_16x16x32_bf16 v[112:115], v[166:169], v[188:191], v[112:115]
	v_mfma_f32_16x16x32_bf16 v[104:107], v[180:183], v[188:191], v[104:107]
	v_mfma_f32_16x16x32_bf16 v[96:99], v[166:169], v[196:199], v[96:99]
	v_mfma_f32_16x16x32_bf16 v[88:91], v[180:183], v[196:199], v[88:91]
	v_mfma_f32_16x16x32_bf16 v[80:83], v[166:169], v[204:207], v[80:83]
	v_mfma_f32_16x16x32_bf16 v[72:75], v[180:183], v[204:207], v[72:75]
	v_mfma_f32_16x16x32_bf16 v[68:71], v[166:169], v[226:229], v[68:71]
	v_mfma_f32_16x16x32_bf16 v[64:67], v[180:183], v[226:229], v[64:67]
	s_setprio 0
	s_barrier
	s_add_i32 s22, s45, s28
	v_lshl_add_u64 v[140:141], v[140:141], 0, s[78:79]
	s_mov_b32 m0, s22
	ds_read_b128 v[184:187], v144 offset:49152
	ds_read_b128 v[188:191], v144 offset:50176
	ds_read_b128 v[192:195], v144 offset:51200
	ds_read_b128 v[196:199], v144 offset:52224
	ds_read_b128 v[200:203], v144 offset:53248
	ds_read_b128 v[204:207], v144 offset:54272
	ds_read_b128 v[208:211], v144 offset:55296
	ds_read_b128 v[226:229], v144 offset:56320
	global_load_lds_dwordx4 v[140:141], off
	s_add_i32 m0, s22, 0x2000
	s_add_u32 s20, s20, 0x200080
	v_lshl_add_u64 v[140:141], v[174:175], 0, s[78:79]
	s_addc_u32 s21, s21, 0
	s_add_i32 s22, s46, s28
	global_load_lds_dwordx4 v[140:141], off
	v_lshl_add_u64 v[140:141], s[20:21], 0, v[178:179]
	s_mov_b32 m0, s22
	s_nop 0
	global_load_lds_dwordx4 v[140:141], off
	v_lshl_add_u64 v[140:141], s[20:21], 0, v[130:131]
	s_add_i32 m0, s22, 0x2000
	s_nop 0
	global_load_lds_dwordx4 v[140:141], off
	v_lshl_add_u64 v[140:141], v[212:213], 0, s[78:79]
	s_mov_b32 m0, s35
	s_nop 0
	global_load_lds_dwordx4 v[140:141], off
	v_lshl_add_u64 v[140:141], v[230:231], 0, s[78:79]
	s_mov_b32 m0, s36
	s_nop 0
	global_load_lds_dwordx4 v[140:141], off
	s_waitcnt vmcnt(8)
	s_waitcnt lgkmcnt(0)
	s_barrier
	s_setprio 1
	s_waitcnt lgkmcnt(0)
	v_mfma_f32_16x16x32_bf16 v[60:63], v[146:149], v[184:187], v[60:63]
	v_mfma_f32_16x16x32_bf16 v[56:59], v[154:157], v[184:187], v[56:59]
	v_mfma_f32_16x16x32_bf16 v[52:55], v[146:149], v[192:195], v[52:55]
	v_mfma_f32_16x16x32_bf16 v[44:47], v[154:157], v[192:195], v[44:47]
	v_mfma_f32_16x16x32_bf16 v[36:39], v[146:149], v[200:203], v[36:39]
	v_mfma_f32_16x16x32_bf16 v[28:31], v[154:157], v[200:203], v[28:31]
	v_mfma_f32_16x16x32_bf16 v[20:23], v[146:149], v[208:211], v[20:23]
	v_mfma_f32_16x16x32_bf16 v[12:15], v[154:157], v[208:211], v[12:15]
	v_mfma_f32_16x16x32_bf16 v[60:63], v[150:153], v[188:191], v[60:63]
	v_mfma_f32_16x16x32_bf16 v[56:59], v[158:161], v[188:191], v[56:59]
	v_mfma_f32_16x16x32_bf16 v[52:55], v[150:153], v[196:199], v[52:55]
	v_mfma_f32_16x16x32_bf16 v[44:47], v[158:161], v[196:199], v[44:47]
	v_mfma_f32_16x16x32_bf16 v[36:39], v[150:153], v[204:207], v[36:39]
	v_mfma_f32_16x16x32_bf16 v[28:31], v[158:161], v[204:207], v[28:31]
	v_mfma_f32_16x16x32_bf16 v[20:23], v[150:153], v[226:229], v[20:23]
	v_mfma_f32_16x16x32_bf16 v[12:15], v[158:161], v[226:229], v[12:15]
	s_setprio 0
	s_setprio 1
	v_mfma_f32_16x16x32_bf16 v[48:51], v[162:165], v[184:187], v[48:51]
	v_mfma_f32_16x16x32_bf16 v[40:43], v[170:173], v[184:187], v[40:43]
	v_mfma_f32_16x16x32_bf16 v[32:35], v[162:165], v[192:195], v[32:35]
	v_mfma_f32_16x16x32_bf16 v[24:27], v[170:173], v[192:195], v[24:27]
	v_mfma_f32_16x16x32_bf16 v[16:19], v[162:165], v[200:203], v[16:19]
	v_mfma_f32_16x16x32_bf16 v[8:11], v[170:173], v[200:203], v[8:11]
	v_mfma_f32_16x16x32_bf16 v[4:7], v[162:165], v[208:211], v[4:7]
	v_mfma_f32_16x16x32_bf16 v[0:3], v[170:173], v[208:211], v[0:3]
	v_mfma_f32_16x16x32_bf16 v[48:51], v[166:169], v[188:191], v[48:51]
	v_mfma_f32_16x16x32_bf16 v[40:43], v[180:183], v[188:191], v[40:43]
	v_mfma_f32_16x16x32_bf16 v[32:35], v[166:169], v[196:199], v[32:35]
	v_mfma_f32_16x16x32_bf16 v[24:27], v[180:183], v[196:199], v[24:27]
	v_mfma_f32_16x16x32_bf16 v[16:19], v[166:169], v[204:207], v[16:19]
	v_mfma_f32_16x16x32_bf16 v[8:11], v[180:183], v[204:207], v[8:11]
	v_mfma_f32_16x16x32_bf16 v[4:7], v[166:169], v[226:229], v[4:7]
	v_mfma_f32_16x16x32_bf16 v[0:3], v[180:183], v[226:229], v[0:3]
	s_setprio 0
	s_barrier
	s_add_i32 s44, s44, 2
	s_add_u32 s18, s18, 0x100
	s_addc_u32 s19, s19, 0
	s_add_u32 s42, s42, 0x100
	s_addc_u32 s43, s43, 0
	s_cmpk_gt_u32 s44, 0x7d
